# loop-edge edit: attention j-loop issues the next tile's K fragment LDS reads at the loop head, above the skip-vote LDS test
# baseline (speedup 1.0000x reference)
; #define LAS __attribute__((address_space(3)))
; __device__ __forceinline__ void attn_unit(LAS unsigned char* lds, const bf16_t* __restrict__ proj, bf16_t* __restrict__ y, int b, int h, int qb,
;                                           float lam, const float* __restrict__ subln, float post_scale, const unsigned* __restrict__ kmax2) {
;     ...
;     for (;; --j) {
;         bool more = j > 1;
;         if (more && j != jend) {
;             const unsigned v0 = *(LAS volatile unsigned*)(FLG + ((j + 1) & 1) * 8), v1 = *(LAS volatile unsigned*)(FLG + ((j + 1) & 1) * 8 + 4);
;             more = !(v0 == 0x01010101u && v1 == 0x01010101u);
;         }
;         if (!more) break;
.LBB0_404:
	s_add_i32 s18, s23, s33
	s_add_i32 s16, s18, 64
	s_and_b32 s16, s16, 1
	s_mul_i32 s17, s16, 0x4400
	v_add_u32_e32 v15, s17, v191
	ds_read_b128 v[2:5], v15
	ds_read_b128 v[6:9], v15 offset:32
	ds_read_b128 v[10:13], v15 offset:8704
	ds_read_b128 v[172:175], v15 offset:8736
	s_add_i32 s19, s18, 0x41
	s_cmp_gt_i32 s19, 1
	s_cselect_b64 s[14:15], -1, 0
	s_cmp_lt_i32 s19, 2
	s_cselect_b64 s[16:17], -1, 0
	s_cmp_eq_u32 s33, 0
	s_cselect_b64 s[38:39], -1, 0
	s_or_b64 s[16:17], s[16:17], s[38:39]
	s_and_b64 vcc, exec, s[16:17]
	s_cbranch_vccnz .LBB0_407
	s_andn2_b32 s14, 8, s21
	s_add_i32 s14, s14, 0
	s_add_i32 s14, s14, 0x23460
	v_mov_b32_e32 v14, s14
	ds_read_b32 v176, v14
	ds_read_b32 v177, v14 offset:4
	s_mov_b32 s14, 0x1010101
	s_waitcnt lgkmcnt(1)
	v_cmp_ne_u32_e32 vcc, s14, v176
	s_waitcnt lgkmcnt(0)
	v_cmp_ne_u32_e64 s[44:45], s14, v177
	s_or_b64 s[14:15], vcc, s[44:45]
	s_mov_b64 s[16:17], -1
	s_and_b64 vcc, exec, s[14:15]
	s_cbranch_vccz .LBB0_408

.LBB0_408:
	s_waitcnt lgkmcnt(0)
	s_add_i32 s37, s11, -1
	s_cbranch_execnz .LBB0_419
.LBB0_409:
	s_add_i32 s16, s18, 64
	s_and_b32 s16, s16, 1
	v_add_u32_e32 v0, s24, v218
	v_cvt_f32_i32_e32 v0, v0
	v_fma_f32 v0, v168, v0, -v193
	v_add_f32_e32 v14, v170, v0
	v_fma_f32 v96, 0, v168, v0
	v_fma_f32 v80, 0, v168, v14
	v_add_f32_e32 v97, v168, v0
	v_add_f32_e32 v81, v168, v14
	v_pk_fma_f32 v[98:99], v[168:169], s[48:49], v[0:1] op_sel_hi:[1,1,0]
	v_pk_fma_f32 v[82:83], v[168:169], s[48:49], v[14:15] op_sel_hi:[1,1,0]
	v_pk_fma_f32 v[100:101], v[168:169], s[58:59], v[0:1] op_sel_hi:[1,1,0]
	v_pk_fma_f32 v[84:85], v[168:169], s[58:59], v[14:15] op_sel_hi:[1,1,0]
	v_pk_fma_f32 v[102:103], v[168:169], s[28:29], v[0:1] op_sel_hi:[1,1,0]
	v_pk_fma_f32 v[86:87], v[168:169], s[28:29], v[14:15] op_sel_hi:[1,1,0]
	v_pk_fma_f32 v[104:105], v[168:169], s[86:87], v[0:1] op_sel_hi:[1,1,0]
	v_pk_fma_f32 v[88:89], v[168:169], s[86:87], v[14:15] op_sel_hi:[1,1,0]
	v_pk_fma_f32 v[106:107], v[168:169], s[90:91], v[0:1] op_sel_hi:[1,1,0]
	v_pk_fma_f32 v[90:91], v[168:169], s[90:91], v[14:15] op_sel_hi:[1,1,0]
	v_pk_fma_f32 v[108:109], v[168:169], s[84:85], v[0:1] op_sel_hi:[1,1,0]
	v_pk_fma_f32 v[92:93], v[168:169], s[84:85], v[14:15] op_sel_hi:[1,1,0]
	v_pk_fma_f32 v[110:111], v[168:169], s[12:13], v[0:1] op_sel_hi:[1,1,0]
	v_pk_fma_f32 v[94:95], v[168:169], s[12:13], v[14:15] op_sel_hi:[1,1,0]
	s_waitcnt lgkmcnt(1)
	s_nop 0
	v_mfma_f32_32x32x16_bf16 v[80:95], v[10:13], v[112:115], v[80:95]
	v_mfma_f32_32x32x16_bf16 v[96:111], v[2:5], v[112:115], v[96:111]
	s_waitcnt lgkmcnt(0)
	v_mfma_f32_32x32x16_bf16 v[80:95], v[172:175], v[116:119], v[80:95]
	ds_read_b128 v[2:5], v15 offset:64
	ds_read_b128 v[10:13], v15 offset:96
	ds_read_b128 v[172:175], v15 offset:8768
	ds_read_b128 v[176:179], v15 offset:8800
	v_mfma_f32_32x32x16_bf16 v[96:111], v[6:9], v[116:119], v[96:111]
	s_waitcnt lgkmcnt(3)
	v_mfma_f32_32x32x16_bf16 v[96:111], v[2:5], v[120:123], v[96:111]
	s_waitcnt lgkmcnt(1)
	v_mfma_f32_32x32x16_bf16 v[80:95], v[172:175], v[120:123], v[80:95]
	v_mfma_f32_32x32x16_bf16 v[96:111], v[10:13], v[124:127], v[96:111]
	s_waitcnt lgkmcnt(0)
	v_mfma_f32_32x32x16_bf16 v[80:95], v[176:179], v[124:127], v[80:95]
	s_cmp_lg_u32 s27, s33
	s_cselect_b64 s[38:39], -1, 0
	s_cmp_le_i32 s19, s10
	s_cselect_b64 s[44:45], -1, 0
	s_and_b64 s[38:39], s[44:45], s[38:39]
	s_and_b64 vcc, exec, s[38:39]
	s_cbranch_vccnz .LBB0_411
	v_add_u32_e32 v0, s24, v207
	v_add_u32_e32 v2, 0x1000, v0
	v_cmp_le_i32_e32 vcc, v2, v162
	v_cmp_lt_i32_e64 s[44:45], s34, v2
	v_add_u32_e32 v3, 0x1020, v0
	s_and_b64 vcc, vcc, s[44:45]
	v_cndmask_b32_e32 v96, v214, v96, vcc
	v_cmp_le_i32_e32 vcc, v3, v162
	v_cmp_lt_i32_e64 s[44:45], s34, v3
	s_and_b64 vcc, vcc, s[44:45]
	v_cndmask_b32_e32 v80, v214, v80, vcc
	v_cmp_lt_i32_e32 vcc, v2, v162
	v_cmp_lt_i32_e64 s[44:45], s36, v2
	v_add_u32_e32 v3, 0x1021, v0
	s_and_b64 vcc, vcc, s[44:45]
	v_cndmask_b32_e32 v97, v214, v97, vcc
	v_cmp_le_i32_e32 vcc, v3, v162
	v_cmp_lt_i32_e64 s[44:45], s34, v3
	s_and_b64 vcc, vcc, s[44:45]
	v_add_u32_e32 v2, 0x1002, v0
	v_cndmask_b32_e32 v81, v214, v81, vcc
	v_cmp_le_i32_e32 vcc, v2, v162
	v_cmp_lt_i32_e64 s[44:45], s34, v2
	v_add_u32_e32 v3, 0x1022, v0
	s_and_b64 vcc, vcc, s[44:45]
	v_cndmask_b32_e32 v98, v214, v98, vcc
	v_cmp_le_i32_e32 vcc, v3, v162
	v_cmp_lt_i32_e64 s[44:45], s34, v3
	s_and_b64 vcc, vcc, s[44:45]
	v_add_u32_e32 v2, 0x1003, v0
	v_cndmask_b32_e32 v82, v214, v82, vcc
	v_cmp_le_i32_e32 vcc, v2, v162
	v_cmp_lt_i32_e64 s[44:45], s34, v2
	v_add_u32_e32 v3, 0x1023, v0
	s_and_b64 vcc, vcc, s[44:45]
	v_cndmask_b32_e32 v99, v214, v99, vcc
	v_cmp_le_i32_e32 vcc, v3, v162
	v_cmp_lt_i32_e64 s[44:45], s34, v3
	s_and_b64 vcc, vcc, s[44:45]
	v_add_u32_e32 v2, 0x1008, v0
	v_cndmask_b32_e32 v83, v214, v83, vcc
	v_cmp_le_i32_e32 vcc, v2, v162
	v_cmp_lt_i32_e64 s[44:45], s34, v2
	v_add_u32_e32 v3, 0x1028, v0
	s_and_b64 vcc, vcc, s[44:45]
	v_cndmask_b32_e32 v100, v214, v100, vcc
	v_cmp_le_i32_e32 vcc, v3, v162
	v_cmp_lt_i32_e64 s[44:45], s34, v3
	s_and_b64 vcc, vcc, s[44:45]
	v_add_u32_e32 v2, 0x1009, v0
	v_cndmask_b32_e32 v84, v214, v84, vcc
	v_cmp_le_i32_e32 vcc, v2, v162
	v_cmp_lt_i32_e64 s[44:45], s34, v2
	v_add_u32_e32 v3, 0x1029, v0
	s_and_b64 vcc, vcc, s[44:45]
	v_cndmask_b32_e32 v101, v214, v101, vcc
	v_cmp_le_i32_e32 vcc, v3, v162
	v_cmp_lt_i32_e64 s[44:45], s34, v3
	s_and_b64 vcc, vcc, s[44:45]
	v_add_u32_e32 v2, 0x100a, v0
	v_cndmask_b32_e32 v85, v214, v85, vcc
	v_cmp_le_i32_e32 vcc, v2, v162
	v_cmp_lt_i32_e64 s[44:45], s34, v2
	v_add_u32_e32 v3, 0x102a, v0
	s_and_b64 vcc, vcc, s[44:45]
	v_cndmask_b32_e32 v102, v214, v102, vcc
	v_cmp_le_i32_e32 vcc, v3, v162
	v_cmp_lt_i32_e64 s[44:45], s34, v3
	s_and_b64 vcc, vcc, s[44:45]
	v_add_u32_e32 v2, 0x100b, v0
	v_cndmask_b32_e32 v86, v214, v86, vcc
	v_cmp_le_i32_e32 vcc, v2, v162
	v_cmp_lt_i32_e64 s[44:45], s34, v2
	v_add_u32_e32 v3, 0x102b, v0
	s_and_b64 vcc, vcc, s[44:45]
	v_cndmask_b32_e32 v103, v214, v103, vcc
	v_cmp_le_i32_e32 vcc, v3, v162
	v_cmp_lt_i32_e64 s[44:45], s34, v3
	s_and_b64 vcc, vcc, s[44:45]
	v_add_u32_e32 v2, 0x1010, v0
	v_cndmask_b32_e32 v87, v214, v87, vcc
	v_cmp_le_i32_e32 vcc, v2, v162
	v_cmp_lt_i32_e64 s[44:45], s34, v2
	v_add_u32_e32 v3, 0x1030, v0
	s_and_b64 vcc, vcc, s[44:45]
	v_cndmask_b32_e32 v104, v214, v104, vcc
	v_cmp_le_i32_e32 vcc, v3, v162
	v_cmp_lt_i32_e64 s[44:45], s34, v3
	s_and_b64 vcc, vcc, s[44:45]
	v_add_u32_e32 v2, 0x1011, v0
	v_cndmask_b32_e32 v88, v214, v88, vcc
	v_cmp_le_i32_e32 vcc, v2, v162
	v_cmp_lt_i32_e64 s[44:45], s34, v2
	v_add_u32_e32 v3, 0x1031, v0
	s_and_b64 vcc, vcc, s[44:45]
	v_cndmask_b32_e32 v105, v214, v105, vcc
	v_cmp_le_i32_e32 vcc, v3, v162
	v_cmp_lt_i32_e64 s[44:45], s34, v3
	s_and_b64 vcc, vcc, s[44:45]
	v_add_u32_e32 v2, 0x1012, v0
	v_cndmask_b32_e32 v89, v214, v89, vcc
	v_cmp_le_i32_e32 vcc, v2, v162
	v_cmp_lt_i32_e64 s[44:45], s34, v2
	v_add_u32_e32 v3, 0x1032, v0
	s_and_b64 vcc, vcc, s[44:45]
	v_cndmask_b32_e32 v106, v214, v106, vcc
	v_cmp_le_i32_e32 vcc, v3, v162
	v_cmp_lt_i32_e64 s[44:45], s34, v3
	s_and_b64 vcc, vcc, s[44:45]
	v_add_u32_e32 v2, 0x1013, v0
	v_cndmask_b32_e32 v90, v214, v90, vcc
	v_cmp_le_i32_e32 vcc, v2, v162
	v_cmp_lt_i32_e64 s[44:45], s34, v2
	v_add_u32_e32 v3, 0x1033, v0
	s_and_b64 vcc, vcc, s[44:45]
	v_cndmask_b32_e32 v107, v214, v107, vcc
	v_cmp_le_i32_e32 vcc, v3, v162
	v_cmp_lt_i32_e64 s[44:45], s34, v3
	s_and_b64 vcc, vcc, s[44:45]
	v_add_u32_e32 v2, 0x1018, v0
	v_cndmask_b32_e32 v91, v214, v91, vcc
	v_cmp_le_i32_e32 vcc, v2, v162
	v_cmp_lt_i32_e64 s[44:45], s34, v2
	v_add_u32_e32 v3, 0x1038, v0
	s_and_b64 vcc, vcc, s[44:45]
	v_cndmask_b32_e32 v108, v214, v108, vcc
	v_cmp_le_i32_e32 vcc, v3, v162
	v_cmp_lt_i32_e64 s[44:45], s34, v3
	s_and_b64 vcc, vcc, s[44:45]
	v_add_u32_e32 v2, 0x1019, v0
	v_cndmask_b32_e32 v92, v214, v92, vcc
	v_cmp_le_i32_e32 vcc, v2, v162
	v_cmp_lt_i32_e64 s[44:45], s34, v2
	v_add_u32_e32 v3, 0x1039, v0
	s_and_b64 vcc, vcc, s[44:45]
	v_cndmask_b32_e32 v109, v214, v109, vcc
	v_cmp_le_i32_e32 vcc, v3, v162
	v_cmp_lt_i32_e64 s[44:45], s34, v3
	s_and_b64 vcc, vcc, s[44:45]
	v_add_u32_e32 v2, 0x101a, v0
	v_cndmask_b32_e32 v93, v214, v93, vcc
	v_cmp_le_i32_e32 vcc, v2, v162
	v_cmp_lt_i32_e64 s[44:45], s34, v2
	v_add_u32_e32 v3, 0x103a, v0
	s_and_b64 vcc, vcc, s[44:45]
	v_cndmask_b32_e32 v110, v214, v110, vcc
	v_cmp_le_i32_e32 vcc, v3, v162
	v_cmp_lt_i32_e64 s[44:45], s34, v3
	s_and_b64 vcc, vcc, s[44:45]
	v_add_u32_e32 v2, 0x101b, v0
	v_cndmask_b32_e32 v94, v214, v94, vcc
	v_cmp_le_i32_e32 vcc, v2, v162
	v_cmp_lt_i32_e64 s[44:45], s34, v2
	v_add_u32_e32 v0, 0x103b, v0
	s_and_b64 vcc, vcc, s[44:45]
	v_cndmask_b32_e32 v111, v214, v111, vcc
	v_cmp_le_i32_e32 vcc, v0, v162
	v_cmp_lt_i32_e64 s[44:45], s34, v0
	s_and_b64 vcc, vcc, s[44:45]
	v_cndmask_b32_e32 v95, v214, v95, vcc
